# K-loop heads aligned to 64 bytes (code placement), on top of mask+wait edits
# speedup vs baseline: 1.0017x; 1.0017x over previous
.LBB0_552:
	s_mov_b32 s17, s9
	s_lshl_b64 s[20:21], s[16:17], 1
	s_add_u32 s20, s58, s20
	s_addc_u32 s21, s59, s21
	s_and_b64 s[22:23], s[6:7], exec
	s_mov_b32 s19, s9
	s_cselect_b32 s17, s21, s27
	s_cselect_b32 s54, s20, s26
	s_lshl_b64 s[22:23], s[18:19], 1
	s_add_u32 s22, s93, s22
	v_readlane_b32 s19, v250, 4
	s_addc_u32 s23, s19, s23
	s_and_b64 s[28:29], s[6:7], exec
	s_cselect_b32 s19, s23, s25
	s_cselect_b32 s55, s22, s24
	s_add_u32 s56, s24, 0x2c0000
	s_addc_u32 s57, s25, 0
	s_add_u32 s24, s26, 0x404000
	v_mov_b32_e32 v0, 0
	s_addc_u32 s25, s27, 0
	s_mov_b32 s62, -2
	v_mov_b32_e32 v1, 0
	v_mov_b64_e32 v[2:3], 0
	v_mov_b64_e32 v[4:5], 0
	v_mov_b64_e32 v[6:7], 0
	v_mov_b64_e32 v[8:9], 0
	v_mov_b64_e32 v[10:11], 0
	v_mov_b64_e32 v[12:13], 0
	v_mov_b64_e32 v[14:15], 0
	v_mov_b64_e32 v[16:17], 0
	v_mov_b64_e32 v[18:19], 0
	v_mov_b64_e32 v[20:21], 0
	v_mov_b64_e32 v[22:23], 0
	v_mov_b64_e32 v[24:25], 0
	v_mov_b64_e32 v[26:27], 0
	v_mov_b64_e32 v[28:29], 0
	v_mov_b64_e32 v[30:31], 0
	v_mov_b64_e32 v[32:33], 0
	v_mov_b64_e32 v[34:35], 0
	v_mov_b64_e32 v[36:37], 0
	v_mov_b64_e32 v[38:39], 0
	v_mov_b64_e32 v[40:41], 0
	v_mov_b64_e32 v[42:43], 0
	v_mov_b64_e32 v[44:45], 0
	v_mov_b64_e32 v[46:47], 0
	v_mov_b64_e32 v[48:49], 0
	v_mov_b64_e32 v[50:51], 0
	v_mov_b64_e32 v[52:53], 0
	v_mov_b64_e32 v[54:55], 0
	v_mov_b64_e32 v[56:57], 0
	v_mov_b64_e32 v[58:59], 0
	v_mov_b64_e32 v[60:61], 0
	v_mov_b64_e32 v[62:63], 0
	v_mov_b64_e32 v[64:65], 0
	v_mov_b64_e32 v[66:67], 0
	v_mov_b64_e32 v[68:69], 0
	v_mov_b64_e32 v[70:71], 0
	v_mov_b64_e32 v[72:73], 0
	v_mov_b64_e32 v[74:75], 0
	v_mov_b64_e32 v[76:77], 0
	v_mov_b64_e32 v[78:79], 0
	v_mov_b64_e32 v[80:81], 0
	v_mov_b64_e32 v[82:83], 0
	v_mov_b64_e32 v[84:85], 0
	v_mov_b64_e32 v[86:87], 0
	v_mov_b64_e32 v[88:89], 0
	v_mov_b64_e32 v[90:91], 0
	v_mov_b64_e32 v[92:93], 0
	v_mov_b64_e32 v[94:95], 0
	v_mov_b64_e32 v[96:97], 0
	v_mov_b64_e32 v[98:99], 0
	v_mov_b64_e32 v[100:101], 0
	v_mov_b64_e32 v[102:103], 0
	v_mov_b64_e32 v[104:105], 0
	v_mov_b64_e32 v[106:107], 0
	v_mov_b64_e32 v[108:109], 0
	v_mov_b64_e32 v[110:111], 0
	v_mov_b64_e32 v[112:113], 0
	v_mov_b64_e32 v[114:115], 0
	v_mov_b64_e32 v[116:117], 0
	v_mov_b64_e32 v[118:119], 0
	v_mov_b64_e32 v[120:121], 0
	v_mov_b64_e32 v[122:123], 0
	v_mov_b64_e32 v[124:125], 0
	v_mov_b64_e32 v[126:127], 0
	.p2align 6

.LBB0_630:
	s_mov_b32 s29, s15
	s_lshl_b64 s[30:31], s[28:29], 1
	s_add_u32 s30, s60, s30
	s_addc_u32 s31, s61, s31
	s_and_b64 s[36:37], exec, s[10:11]
	s_cselect_b32 s17, s31, s9
	s_cselect_b32 s29, s30, s8
	s_lshl_b64 s[34:35], s[34:35], 1
	s_add_u32 s34, s46, s34
	s_addc_u32 s35, s47, s35
	s_and_b64 s[10:11], exec, s[10:11]
	s_cselect_b32 s38, s35, s7
	s_cselect_b32 s39, s34, s6
	s_add_u32 s40, s6, 0x80000
	s_addc_u32 s41, s7, 0
	s_add_u32 s6, s8, 0x404000
	v_mov_b32_e32 v56, 0
	s_addc_u32 s7, s9, 0
	s_mov_b32 s42, -2
	v_mov_b64_e32 v[0:1], 0
	v_mov_b64_e32 v[2:3], 0
	v_mov_b64_e32 v[4:5], 0
	v_mov_b64_e32 v[6:7], 0
	v_mov_b64_e32 v[8:9], 0
	v_mov_b64_e32 v[10:11], 0
	v_mov_b64_e32 v[12:13], 0
	v_mov_b64_e32 v[14:15], 0
	v_mov_b64_e32 v[16:17], 0
	v_mov_b64_e32 v[18:19], 0
	v_mov_b64_e32 v[20:21], 0
	v_mov_b64_e32 v[22:23], 0
	v_mov_b64_e32 v[24:25], 0
	v_mov_b64_e32 v[26:27], 0
	v_mov_b64_e32 v[28:29], 0
	v_mov_b64_e32 v[30:31], 0
	v_mov_b64_e32 v[32:33], 0
	v_mov_b64_e32 v[34:35], 0
	v_mov_b64_e32 v[36:37], 0
	v_mov_b64_e32 v[38:39], 0
	v_mov_b64_e32 v[40:41], 0
	v_mov_b64_e32 v[42:43], 0
	v_mov_b64_e32 v[44:45], 0
	v_mov_b64_e32 v[46:47], 0
	v_mov_b64_e32 v[48:49], 0
	v_mov_b64_e32 v[50:51], 0
	v_mov_b64_e32 v[52:53], 0
	v_mov_b64_e32 v[54:55], 0
	v_mov_b32_e32 v57, 0
	v_mov_b64_e32 v[58:59], 0
	v_mov_b64_e32 v[60:61], 0
	v_mov_b64_e32 v[62:63], 0
	v_mov_b64_e32 v[64:65], 0
	v_mov_b64_e32 v[66:67], 0
	v_mov_b64_e32 v[68:69], 0
	v_mov_b64_e32 v[70:71], 0
	v_mov_b64_e32 v[72:73], 0
	v_mov_b64_e32 v[74:75], 0
	v_mov_b64_e32 v[76:77], 0
	v_mov_b64_e32 v[78:79], 0
	v_mov_b64_e32 v[80:81], 0
	v_mov_b64_e32 v[82:83], 0
	v_mov_b64_e32 v[84:85], 0
	v_mov_b64_e32 v[86:87], 0
	v_mov_b64_e32 v[88:89], 0
	v_mov_b64_e32 v[90:91], 0
	v_mov_b64_e32 v[92:93], 0
	v_mov_b64_e32 v[94:95], 0
	v_mov_b64_e32 v[96:97], 0
	v_mov_b64_e32 v[98:99], 0
	v_mov_b64_e32 v[100:101], 0
	v_mov_b64_e32 v[102:103], 0
	v_mov_b64_e32 v[104:105], 0
	v_mov_b64_e32 v[106:107], 0
	v_mov_b64_e32 v[108:109], 0
	v_mov_b64_e32 v[110:111], 0
	v_mov_b64_e32 v[112:113], 0
	v_mov_b64_e32 v[114:115], 0
	v_mov_b64_e32 v[116:117], 0
	v_mov_b64_e32 v[118:119], 0
	v_mov_b64_e32 v[120:121], 0
	v_mov_b64_e32 v[122:123], 0
	v_mov_b64_e32 v[124:125], 0
	v_mov_b64_e32 v[126:127], 0
	.p2align 6

.LBB0_731:
	s_mov_b32 s17, s9
	s_lshl_b64 s[20:21], s[16:17], 1
	s_add_u32 s20, s58, s20
	s_addc_u32 s21, s59, s21
	s_and_b64 s[22:23], s[6:7], exec
	s_mov_b32 s19, s9
	s_cselect_b32 s17, s21, s27
	s_cselect_b32 s54, s20, s26
	s_lshl_b64 s[22:23], s[18:19], 1
	s_add_u32 s22, s72, s22
	s_addc_u32 s23, s73, s23
	s_and_b64 s[28:29], s[6:7], exec
	s_cselect_b32 s19, s23, s25
	s_cselect_b32 s55, s22, s24
	s_add_u32 s56, s24, 0x1b0000
	s_addc_u32 s74, s25, 0
	s_add_u32 s24, s26, 0x404000
	v_mov_b32_e32 v32, 0
	s_addc_u32 s25, s27, 0
	s_mov_b32 s75, -2
	v_mov_b64_e32 v[0:1], 0
	v_mov_b64_e32 v[2:3], 0
	v_mov_b64_e32 v[4:5], 0
	v_mov_b64_e32 v[6:7], 0
	v_mov_b64_e32 v[8:9], 0
	v_mov_b64_e32 v[10:11], 0
	v_mov_b64_e32 v[12:13], 0
	v_mov_b64_e32 v[14:15], 0
	v_mov_b64_e32 v[16:17], 0
	v_mov_b64_e32 v[18:19], 0
	v_mov_b64_e32 v[20:21], 0
	v_mov_b64_e32 v[22:23], 0
	v_mov_b64_e32 v[24:25], 0
	v_mov_b64_e32 v[26:27], 0
	v_mov_b64_e32 v[28:29], 0
	v_mov_b64_e32 v[30:31], 0
	v_mov_b32_e32 v33, 0
	v_mov_b64_e32 v[34:35], 0
	v_mov_b64_e32 v[36:37], 0
	v_mov_b64_e32 v[38:39], 0
	v_mov_b64_e32 v[40:41], 0
	v_mov_b64_e32 v[42:43], 0
	v_mov_b64_e32 v[44:45], 0
	v_mov_b64_e32 v[46:47], 0
	v_mov_b64_e32 v[48:49], 0
	v_mov_b64_e32 v[50:51], 0
	v_mov_b64_e32 v[52:53], 0
	v_mov_b64_e32 v[54:55], 0
	v_mov_b64_e32 v[56:57], 0
	v_mov_b64_e32 v[58:59], 0
	v_mov_b64_e32 v[60:61], 0
	v_mov_b64_e32 v[62:63], 0
	v_mov_b64_e32 v[64:65], 0
	v_mov_b64_e32 v[66:67], 0
	v_mov_b64_e32 v[68:69], 0
	v_mov_b64_e32 v[70:71], 0
	v_mov_b64_e32 v[72:73], 0
	v_mov_b64_e32 v[74:75], 0
	v_mov_b64_e32 v[76:77], 0
	v_mov_b64_e32 v[78:79], 0
	v_mov_b64_e32 v[80:81], 0
	v_mov_b64_e32 v[82:83], 0
	v_mov_b64_e32 v[84:85], 0
	v_mov_b64_e32 v[86:87], 0
	v_mov_b64_e32 v[88:89], 0
	v_mov_b64_e32 v[90:91], 0
	v_mov_b64_e32 v[92:93], 0
	v_mov_b64_e32 v[94:95], 0
	v_mov_b64_e32 v[96:97], 0
	v_mov_b64_e32 v[98:99], 0
	v_mov_b64_e32 v[100:101], 0
	v_mov_b64_e32 v[102:103], 0
	v_mov_b64_e32 v[104:105], 0
	v_mov_b64_e32 v[106:107], 0
	v_mov_b64_e32 v[108:109], 0
	v_mov_b64_e32 v[110:111], 0
	v_mov_b64_e32 v[112:113], 0
	v_mov_b64_e32 v[114:115], 0
	v_mov_b64_e32 v[116:117], 0
	v_mov_b64_e32 v[118:119], 0
	v_mov_b64_e32 v[120:121], 0
	v_mov_b64_e32 v[122:123], 0
	v_mov_b64_e32 v[124:125], 0
	v_mov_b64_e32 v[126:127], 0
	.p2align 6

.LBB0_1281:
	s_mov_b32 s31, s13
	s_lshl_b64 s[34:35], s[30:31], 1
	s_add_u32 s34, s64, s34
	s_addc_u32 s35, s65, s35
	s_and_b64 s[38:39], exec, s[10:11]
	s_cselect_b32 s12, s35, s9
	s_cselect_b32 s15, s34, s8
	s_lshl_b64 s[36:37], s[36:37], 1
	s_add_u32 s36, s91, s36
	s_addc_u32 s37, s92, s37
	s_and_b64 s[10:11], exec, s[10:11]
	s_cselect_b32 s31, s37, s7
	s_cselect_b32 s41, s36, s6
	s_add_u32 s42, s6, 0x80000
	s_addc_u32 s43, s7, 0
	s_add_u32 s6, s8, 0x404000
	v_mov_b32_e32 v56, 0
	s_addc_u32 s7, s9, 0
	s_mov_b32 s44, -2
	v_mov_b64_e32 v[0:1], 0
	v_mov_b64_e32 v[2:3], 0
	v_mov_b64_e32 v[4:5], 0
	v_mov_b64_e32 v[6:7], 0
	v_mov_b64_e32 v[8:9], 0
	v_mov_b64_e32 v[10:11], 0
	v_mov_b64_e32 v[12:13], 0
	v_mov_b64_e32 v[14:15], 0
	v_mov_b64_e32 v[16:17], 0
	v_mov_b64_e32 v[18:19], 0
	v_mov_b64_e32 v[20:21], 0
	v_mov_b64_e32 v[22:23], 0
	v_mov_b64_e32 v[24:25], 0
	v_mov_b64_e32 v[26:27], 0
	v_mov_b64_e32 v[28:29], 0
	v_mov_b64_e32 v[30:31], 0
	v_mov_b64_e32 v[32:33], 0
	v_mov_b64_e32 v[34:35], 0
	v_mov_b64_e32 v[36:37], 0
	v_mov_b64_e32 v[38:39], 0
	v_mov_b64_e32 v[40:41], 0
	v_mov_b64_e32 v[42:43], 0
	v_mov_b64_e32 v[44:45], 0
	v_mov_b64_e32 v[46:47], 0
	v_mov_b64_e32 v[48:49], 0
	v_mov_b64_e32 v[50:51], 0
	v_mov_b64_e32 v[52:53], 0
	v_mov_b64_e32 v[54:55], 0
	v_mov_b32_e32 v57, 0
	v_mov_b64_e32 v[58:59], 0
	v_mov_b64_e32 v[60:61], 0
	v_mov_b64_e32 v[62:63], 0
	v_mov_b64_e32 v[64:65], 0
	v_mov_b64_e32 v[66:67], 0
	v_mov_b64_e32 v[68:69], 0
	v_mov_b64_e32 v[70:71], 0
	v_mov_b64_e32 v[72:73], 0
	v_mov_b64_e32 v[74:75], 0
	v_mov_b64_e32 v[76:77], 0
	v_mov_b64_e32 v[78:79], 0
	v_mov_b64_e32 v[80:81], 0
	v_mov_b64_e32 v[82:83], 0
	v_mov_b64_e32 v[84:85], 0
	v_mov_b64_e32 v[86:87], 0
	v_mov_b64_e32 v[88:89], 0
	v_mov_b64_e32 v[90:91], 0
	v_mov_b64_e32 v[92:93], 0
	v_mov_b64_e32 v[94:95], 0
	v_mov_b64_e32 v[96:97], 0
	v_mov_b64_e32 v[98:99], 0
	v_mov_b64_e32 v[100:101], 0
	v_mov_b64_e32 v[102:103], 0
	v_mov_b64_e32 v[104:105], 0
	v_mov_b64_e32 v[106:107], 0
	v_mov_b64_e32 v[108:109], 0
	v_mov_b64_e32 v[110:111], 0
	v_mov_b64_e32 v[112:113], 0
	v_mov_b64_e32 v[114:115], 0
	v_mov_b64_e32 v[116:117], 0
	v_mov_b64_e32 v[118:119], 0
	v_mov_b64_e32 v[120:121], 0
	v_mov_b64_e32 v[122:123], 0
	v_mov_b64_e32 v[124:125], 0
	v_mov_b64_e32 v[126:127], 0
	.p2align 6

.LBB0_1403:
	s_mov_b32 s17, s9
	s_lshl_b64 s[20:21], s[16:17], 1
	s_add_u32 s20, s58, s20
	s_addc_u32 s21, s59, s21
	s_and_b64 s[22:23], s[6:7], exec
	s_mov_b32 s19, s9
	s_cselect_b32 s8, s21, s27
	s_cselect_b32 s17, s20, s26
	s_lshl_b64 s[22:23], s[18:19], 1
	v_readlane_b32 s19, v250, 17
	s_add_u32 s22, s19, s22
	v_readlane_b32 s19, v250, 4
	s_addc_u32 s23, s19, s23
	s_and_b64 s[28:29], s[6:7], exec
	s_cselect_b32 s19, s23, s25
	s_cselect_b32 s47, s22, s24
	s_add_u32 s50, s24, 0x100
	s_addc_u32 s51, s25, 0
	s_add_u32 s24, s26, 0x404000
	v_mov_b32_e32 v0, 0
	s_addc_u32 s25, s27, 0
	s_mov_b32 s52, -2
	v_mov_b32_e32 v1, 0
	v_mov_b64_e32 v[2:3], 0
	v_mov_b64_e32 v[4:5], 0
	v_mov_b64_e32 v[6:7], 0
	v_mov_b64_e32 v[8:9], 0
	v_mov_b64_e32 v[10:11], 0
	v_mov_b64_e32 v[12:13], 0
	v_mov_b64_e32 v[14:15], 0
	v_mov_b64_e32 v[16:17], 0
	v_mov_b64_e32 v[18:19], 0
	v_mov_b64_e32 v[20:21], 0
	v_mov_b64_e32 v[22:23], 0
	v_mov_b64_e32 v[24:25], 0
	v_mov_b64_e32 v[26:27], 0
	v_mov_b64_e32 v[28:29], 0
	v_mov_b64_e32 v[30:31], 0
	v_mov_b64_e32 v[32:33], 0
	v_mov_b64_e32 v[34:35], 0
	v_mov_b64_e32 v[36:37], 0
	v_mov_b64_e32 v[38:39], 0
	v_mov_b64_e32 v[40:41], 0
	v_mov_b64_e32 v[42:43], 0
	v_mov_b64_e32 v[44:45], 0
	v_mov_b64_e32 v[46:47], 0
	v_mov_b64_e32 v[48:49], 0
	v_mov_b64_e32 v[50:51], 0
	v_mov_b64_e32 v[52:53], 0
	v_mov_b64_e32 v[54:55], 0
	v_mov_b64_e32 v[56:57], 0
	v_mov_b64_e32 v[58:59], 0
	v_mov_b64_e32 v[60:61], 0
	v_mov_b64_e32 v[62:63], 0
	v_mov_b64_e32 v[64:65], 0
	v_mov_b64_e32 v[66:67], 0
	v_mov_b64_e32 v[68:69], 0
	v_mov_b64_e32 v[70:71], 0
	v_mov_b64_e32 v[72:73], 0
	v_mov_b64_e32 v[74:75], 0
	v_mov_b64_e32 v[76:77], 0
	v_mov_b64_e32 v[78:79], 0
	v_mov_b64_e32 v[80:81], 0
	v_mov_b64_e32 v[82:83], 0
	v_mov_b64_e32 v[84:85], 0
	v_mov_b64_e32 v[86:87], 0
	v_mov_b64_e32 v[88:89], 0
	v_mov_b64_e32 v[90:91], 0
	v_mov_b64_e32 v[92:93], 0
	v_mov_b64_e32 v[94:95], 0
	v_mov_b64_e32 v[96:97], 0
	v_mov_b64_e32 v[98:99], 0
	v_mov_b64_e32 v[100:101], 0
	v_mov_b64_e32 v[102:103], 0
	v_mov_b64_e32 v[104:105], 0
	v_mov_b64_e32 v[106:107], 0
	v_mov_b64_e32 v[108:109], 0
	v_mov_b64_e32 v[110:111], 0
	v_mov_b64_e32 v[112:113], 0
	v_mov_b64_e32 v[114:115], 0
	v_mov_b64_e32 v[116:117], 0
	v_mov_b64_e32 v[118:119], 0
	v_mov_b64_e32 v[120:121], 0
	v_mov_b64_e32 v[122:123], 0
	v_mov_b64_e32 v[124:125], 0
	v_mov_b64_e32 v[126:127], 0
	.p2align 6

.LBB0_1511:
	s_mov_b32 s29, s13
	s_lshl_b64 s[34:35], s[28:29], 1
	s_add_u32 s34, s91, s34
	s_addc_u32 s35, s92, s35
	s_and_b64 s[36:37], s[10:11], exec
	s_mov_b32 s31, s13
	s_cselect_b32 s12, s35, s9
	s_cselect_b32 s15, s34, s8
	s_lshl_b64 s[36:37], s[30:31], 1
	s_add_u32 s36, s84, s36
	s_addc_u32 s37, s85, s37
	s_and_b64 s[10:11], s[10:11], exec
	s_cselect_b32 s29, s37, s7
	s_cselect_b32 s31, s36, s6
	s_add_u32 s41, s6, 0x100
	s_addc_u32 s42, s7, 0
	s_add_u32 s6, s8, 0x404000
	v_mov_b32_e32 v56, 0
	s_addc_u32 s7, s9, 0
	s_mov_b32 s43, -2
	v_mov_b64_e32 v[0:1], 0
	v_mov_b64_e32 v[2:3], 0
	v_mov_b64_e32 v[4:5], 0
	v_mov_b64_e32 v[6:7], 0
	v_mov_b64_e32 v[8:9], 0
	v_mov_b64_e32 v[10:11], 0
	v_mov_b64_e32 v[12:13], 0
	v_mov_b64_e32 v[14:15], 0
	v_mov_b64_e32 v[16:17], 0
	v_mov_b64_e32 v[18:19], 0
	v_mov_b64_e32 v[20:21], 0
	v_mov_b64_e32 v[22:23], 0
	v_mov_b64_e32 v[24:25], 0
	v_mov_b64_e32 v[26:27], 0
	v_mov_b64_e32 v[28:29], 0
	v_mov_b64_e32 v[30:31], 0
	v_mov_b64_e32 v[32:33], 0
	v_mov_b64_e32 v[34:35], 0
	v_mov_b64_e32 v[36:37], 0
	v_mov_b64_e32 v[38:39], 0
	v_mov_b64_e32 v[40:41], 0
	v_mov_b64_e32 v[42:43], 0
	v_mov_b64_e32 v[44:45], 0
	v_mov_b64_e32 v[46:47], 0
	v_mov_b64_e32 v[48:49], 0
	v_mov_b64_e32 v[50:51], 0
	v_mov_b64_e32 v[52:53], 0
	v_mov_b64_e32 v[54:55], 0
	v_mov_b32_e32 v57, 0
	v_mov_b64_e32 v[58:59], 0
	v_mov_b64_e32 v[60:61], 0
	v_mov_b64_e32 v[62:63], 0
	v_mov_b64_e32 v[64:65], 0
	v_mov_b64_e32 v[66:67], 0
	v_mov_b64_e32 v[68:69], 0
	v_mov_b64_e32 v[70:71], 0
	v_mov_b64_e32 v[72:73], 0
	v_mov_b64_e32 v[74:75], 0
	v_mov_b64_e32 v[76:77], 0
	v_mov_b64_e32 v[78:79], 0
	v_mov_b64_e32 v[80:81], 0
	v_mov_b64_e32 v[82:83], 0
	v_mov_b64_e32 v[84:85], 0
	v_mov_b64_e32 v[86:87], 0
	v_mov_b64_e32 v[88:89], 0
	v_mov_b64_e32 v[90:91], 0
	v_mov_b64_e32 v[92:93], 0
	v_mov_b64_e32 v[94:95], 0
	v_mov_b64_e32 v[96:97], 0
	v_mov_b64_e32 v[98:99], 0
	v_mov_b64_e32 v[100:101], 0
	v_mov_b64_e32 v[102:103], 0
	v_mov_b64_e32 v[104:105], 0
	v_mov_b64_e32 v[106:107], 0
	v_mov_b64_e32 v[108:109], 0
	v_mov_b64_e32 v[110:111], 0
	v_mov_b64_e32 v[112:113], 0
	v_mov_b64_e32 v[114:115], 0
	v_mov_b64_e32 v[116:117], 0
	v_mov_b64_e32 v[118:119], 0
	v_mov_b64_e32 v[120:121], 0
	v_mov_b64_e32 v[122:123], 0
	v_mov_b64_e32 v[124:125], 0
	v_mov_b64_e32 v[126:127], 0
	.p2align 6

.LBB0_1627:
	s_mov_b32 s17, s9
	s_lshl_b64 s[20:21], s[16:17], 1
	s_add_u32 s20, s58, s20
	s_addc_u32 s21, s59, s21
	s_and_b64 s[22:23], s[6:7], exec
	s_mov_b32 s19, s9
	s_cselect_b32 s17, s21, s27
	s_cselect_b32 s46, s20, s26
	s_lshl_b64 s[22:23], s[18:19], 1
	s_add_u32 s22, s4, s22
	s_addc_u32 s23, s5, s23
	s_and_b64 s[28:29], s[6:7], exec
	s_cselect_b32 s19, s23, s25
	s_cselect_b32 s47, s22, s24
	s_add_u32 s50, s24, 0x2c0000
	s_addc_u32 s51, s25, 0
	s_add_u32 s24, s26, 0x404000
	v_mov_b32_e32 v0, 0
	s_addc_u32 s25, s27, 0
	s_mov_b32 s52, -2
	v_mov_b32_e32 v1, 0
	v_mov_b64_e32 v[2:3], 0
	v_mov_b64_e32 v[4:5], 0
	v_mov_b64_e32 v[6:7], 0
	v_mov_b64_e32 v[8:9], 0
	v_mov_b64_e32 v[10:11], 0
	v_mov_b64_e32 v[12:13], 0
	v_mov_b64_e32 v[14:15], 0
	v_mov_b64_e32 v[16:17], 0
	v_mov_b64_e32 v[18:19], 0
	v_mov_b64_e32 v[20:21], 0
	v_mov_b64_e32 v[22:23], 0
	v_mov_b64_e32 v[24:25], 0
	v_mov_b64_e32 v[26:27], 0
	v_mov_b64_e32 v[28:29], 0
	v_mov_b64_e32 v[30:31], 0
	v_mov_b64_e32 v[32:33], 0
	v_mov_b64_e32 v[34:35], 0
	v_mov_b64_e32 v[36:37], 0
	v_mov_b64_e32 v[38:39], 0
	v_mov_b64_e32 v[40:41], 0
	v_mov_b64_e32 v[42:43], 0
	v_mov_b64_e32 v[44:45], 0
	v_mov_b64_e32 v[46:47], 0
	v_mov_b64_e32 v[48:49], 0
	v_mov_b64_e32 v[50:51], 0
	v_mov_b64_e32 v[52:53], 0
	v_mov_b64_e32 v[54:55], 0
	v_mov_b64_e32 v[56:57], 0
	v_mov_b64_e32 v[58:59], 0
	v_mov_b64_e32 v[60:61], 0
	v_mov_b64_e32 v[62:63], 0
	v_mov_b64_e32 v[64:65], 0
	v_mov_b64_e32 v[66:67], 0
	v_mov_b64_e32 v[68:69], 0
	v_mov_b64_e32 v[70:71], 0
	v_mov_b64_e32 v[72:73], 0
	v_mov_b64_e32 v[74:75], 0
	v_mov_b64_e32 v[76:77], 0
	v_mov_b64_e32 v[78:79], 0
	v_mov_b64_e32 v[80:81], 0
	v_mov_b64_e32 v[82:83], 0
	v_mov_b64_e32 v[84:85], 0
	v_mov_b64_e32 v[86:87], 0
	v_mov_b64_e32 v[88:89], 0
	v_mov_b64_e32 v[90:91], 0
	v_mov_b64_e32 v[92:93], 0
	v_mov_b64_e32 v[94:95], 0
	v_mov_b64_e32 v[96:97], 0
	v_mov_b64_e32 v[98:99], 0
	v_mov_b64_e32 v[100:101], 0
	v_mov_b64_e32 v[102:103], 0
	v_mov_b64_e32 v[104:105], 0
	v_mov_b64_e32 v[106:107], 0
	v_mov_b64_e32 v[108:109], 0
	v_mov_b64_e32 v[110:111], 0
	v_mov_b64_e32 v[112:113], 0
	v_mov_b64_e32 v[114:115], 0
	v_mov_b64_e32 v[116:117], 0
	v_mov_b64_e32 v[118:119], 0
	v_mov_b64_e32 v[120:121], 0
	v_mov_b64_e32 v[122:123], 0
	v_mov_b64_e32 v[124:125], 0
	v_mov_b64_e32 v[126:127], 0
	.p2align 6

.LBB0_1705:
	s_mov_b32 s31, s13
	s_lshl_b64 s[34:35], s[30:31], 1
	s_add_u32 s34, s60, s34
	s_addc_u32 s35, s61, s35
	s_and_b64 s[38:39], exec, s[10:11]
	s_cselect_b32 s12, s35, s9
	s_cselect_b32 s15, s34, s8
	s_lshl_b64 s[36:37], s[36:37], 1
	s_add_u32 s36, s29, s36
	s_addc_u32 s37, s54, s37
	s_and_b64 s[10:11], exec, s[10:11]
	s_cselect_b32 s31, s37, s7
	s_cselect_b32 s41, s36, s6
	s_add_u32 s42, s6, 0x80000
	s_addc_u32 s43, s7, 0
	s_add_u32 s6, s8, 0x404000
	v_mov_b32_e32 v56, 0
	s_addc_u32 s7, s9, 0
	s_mov_b32 s44, -2
	v_mov_b64_e32 v[0:1], 0
	v_mov_b64_e32 v[2:3], 0
	v_mov_b64_e32 v[4:5], 0
	v_mov_b64_e32 v[6:7], 0
	v_mov_b64_e32 v[8:9], 0
	v_mov_b64_e32 v[10:11], 0
	v_mov_b64_e32 v[12:13], 0
	v_mov_b64_e32 v[14:15], 0
	v_mov_b64_e32 v[16:17], 0
	v_mov_b64_e32 v[18:19], 0
	v_mov_b64_e32 v[20:21], 0
	v_mov_b64_e32 v[22:23], 0
	v_mov_b64_e32 v[24:25], 0
	v_mov_b64_e32 v[26:27], 0
	v_mov_b64_e32 v[28:29], 0
	v_mov_b64_e32 v[30:31], 0
	v_mov_b64_e32 v[32:33], 0
	v_mov_b64_e32 v[34:35], 0
	v_mov_b64_e32 v[36:37], 0
	v_mov_b64_e32 v[38:39], 0
	v_mov_b64_e32 v[40:41], 0
	v_mov_b64_e32 v[42:43], 0
	v_mov_b64_e32 v[44:45], 0
	v_mov_b64_e32 v[46:47], 0
	v_mov_b64_e32 v[48:49], 0
	v_mov_b64_e32 v[50:51], 0
	v_mov_b64_e32 v[52:53], 0
	v_mov_b64_e32 v[54:55], 0
	v_mov_b32_e32 v57, 0
	v_mov_b64_e32 v[58:59], 0
	v_mov_b64_e32 v[60:61], 0
	v_mov_b64_e32 v[62:63], 0
	v_mov_b64_e32 v[64:65], 0
	v_mov_b64_e32 v[66:67], 0
	v_mov_b64_e32 v[68:69], 0
	v_mov_b64_e32 v[70:71], 0
	v_mov_b64_e32 v[72:73], 0
	v_mov_b64_e32 v[74:75], 0
	v_mov_b64_e32 v[76:77], 0
	v_mov_b64_e32 v[78:79], 0
	v_mov_b64_e32 v[80:81], 0
	v_mov_b64_e32 v[82:83], 0
	v_mov_b64_e32 v[84:85], 0
	v_mov_b64_e32 v[86:87], 0
	v_mov_b64_e32 v[88:89], 0
	v_mov_b64_e32 v[90:91], 0
	v_mov_b64_e32 v[92:93], 0
	v_mov_b64_e32 v[94:95], 0
	v_mov_b64_e32 v[96:97], 0
	v_mov_b64_e32 v[98:99], 0
	v_mov_b64_e32 v[100:101], 0
	v_mov_b64_e32 v[102:103], 0
	v_mov_b64_e32 v[104:105], 0
	v_mov_b64_e32 v[106:107], 0
	v_mov_b64_e32 v[108:109], 0
	v_mov_b64_e32 v[110:111], 0
	v_mov_b64_e32 v[112:113], 0
	v_mov_b64_e32 v[114:115], 0
	v_mov_b64_e32 v[116:117], 0
	v_mov_b64_e32 v[118:119], 0
	v_mov_b64_e32 v[120:121], 0
	v_mov_b64_e32 v[122:123], 0
	v_mov_b64_e32 v[124:125], 0
	v_mov_b64_e32 v[126:127], 0
	.p2align 6

.LBB0_1998:
	s_mov_b32 s17, s9
	s_lshl_b64 s[20:21], s[16:17], 1
	s_add_u32 s20, s58, s20
	s_addc_u32 s21, s59, s21
	s_and_b64 s[22:23], s[6:7], exec
	s_mov_b32 s19, s9
	s_cselect_b32 s17, s21, s27
	s_cselect_b32 s51, s20, s26
	s_lshl_b64 s[22:23], s[18:19], 1
	s_add_u32 s22, s4, s22
	s_addc_u32 s23, s5, s23
	s_and_b64 s[28:29], s[6:7], exec
	s_cselect_b32 s19, s23, s25
	s_cselect_b32 s52, s22, s24
	s_add_u32 s53, s24, 0x1b0000
	s_addc_u32 s54, s25, 0
	s_add_u32 s24, s26, 0x404000
	v_mov_b32_e32 v32, 0
	s_addc_u32 s25, s27, 0
	s_mov_b32 s55, -2
	v_mov_b64_e32 v[0:1], 0
	v_mov_b64_e32 v[2:3], 0
	v_mov_b64_e32 v[4:5], 0
	v_mov_b64_e32 v[6:7], 0
	v_mov_b64_e32 v[8:9], 0
	v_mov_b64_e32 v[10:11], 0
	v_mov_b64_e32 v[12:13], 0
	v_mov_b64_e32 v[14:15], 0
	v_mov_b64_e32 v[16:17], 0
	v_mov_b64_e32 v[18:19], 0
	v_mov_b64_e32 v[20:21], 0
	v_mov_b64_e32 v[22:23], 0
	v_mov_b64_e32 v[24:25], 0
	v_mov_b64_e32 v[26:27], 0
	v_mov_b64_e32 v[28:29], 0
	v_mov_b64_e32 v[30:31], 0
	v_mov_b32_e32 v33, 0
	v_mov_b64_e32 v[34:35], 0
	v_mov_b64_e32 v[36:37], 0
	v_mov_b64_e32 v[38:39], 0
	v_mov_b64_e32 v[40:41], 0
	v_mov_b64_e32 v[42:43], 0
	v_mov_b64_e32 v[44:45], 0
	v_mov_b64_e32 v[46:47], 0
	v_mov_b64_e32 v[48:49], 0
	v_mov_b64_e32 v[50:51], 0
	v_mov_b64_e32 v[52:53], 0
	v_mov_b64_e32 v[54:55], 0
	v_mov_b64_e32 v[56:57], 0
	v_mov_b64_e32 v[58:59], 0
	v_mov_b64_e32 v[60:61], 0
	v_mov_b64_e32 v[62:63], 0
	v_mov_b64_e32 v[64:65], 0
	v_mov_b64_e32 v[66:67], 0
	v_mov_b64_e32 v[68:69], 0
	v_mov_b64_e32 v[70:71], 0
	v_mov_b64_e32 v[72:73], 0
	v_mov_b64_e32 v[74:75], 0
	v_mov_b64_e32 v[76:77], 0
	v_mov_b64_e32 v[78:79], 0
	v_mov_b64_e32 v[80:81], 0
	v_mov_b64_e32 v[82:83], 0
	v_mov_b64_e32 v[84:85], 0
	v_mov_b64_e32 v[86:87], 0
	v_mov_b64_e32 v[88:89], 0
	v_mov_b64_e32 v[90:91], 0
	v_mov_b64_e32 v[92:93], 0
	v_mov_b64_e32 v[94:95], 0
	v_mov_b64_e32 v[96:97], 0
	v_mov_b64_e32 v[98:99], 0
	v_mov_b64_e32 v[100:101], 0
	v_mov_b64_e32 v[102:103], 0
	v_mov_b64_e32 v[104:105], 0
	v_mov_b64_e32 v[106:107], 0
	v_mov_b64_e32 v[108:109], 0
	v_mov_b64_e32 v[110:111], 0
	v_mov_b64_e32 v[112:113], 0
	v_mov_b64_e32 v[114:115], 0
	v_mov_b64_e32 v[116:117], 0
	v_mov_b64_e32 v[118:119], 0
	v_mov_b64_e32 v[120:121], 0
	v_mov_b64_e32 v[122:123], 0
	v_mov_b64_e32 v[124:125], 0
	v_mov_b64_e32 v[126:127], 0
	.p2align 6

.LBB0_2541:
	s_mov_b32 s29, s11
	s_lshl_b64 s[30:31], s[28:29], 1
	s_add_u32 s30, s64, s30
	s_addc_u32 s31, s65, s31
	s_and_b64 s[36:37], exec, s[8:9]
	s_cselect_b32 s10, s31, s7
	s_cselect_b32 s13, s30, s6
	s_lshl_b64 s[34:35], s[34:35], 1
	s_add_u32 s34, s2, s34
	s_addc_u32 s35, s3, s35
	s_and_b64 s[8:9], exec, s[8:9]
	s_cselect_b32 s29, s35, s1
	s_cselect_b32 s39, s34, s0
	s_add_u32 s40, s0, 0x80000
	s_addc_u32 s41, s1, 0
	s_add_u32 s0, s6, 0x404000
	v_mov_b32_e32 v56, 0
	s_addc_u32 s1, s7, 0
	s_mov_b32 s42, -2
	v_mov_b64_e32 v[0:1], 0
	v_mov_b64_e32 v[2:3], 0
	v_mov_b64_e32 v[4:5], 0
	v_mov_b64_e32 v[6:7], 0
	v_mov_b64_e32 v[8:9], 0
	v_mov_b64_e32 v[10:11], 0
	v_mov_b64_e32 v[12:13], 0
	v_mov_b64_e32 v[14:15], 0
	v_mov_b64_e32 v[16:17], 0
	v_mov_b64_e32 v[18:19], 0
	v_mov_b64_e32 v[20:21], 0
	v_mov_b64_e32 v[22:23], 0
	v_mov_b64_e32 v[24:25], 0
	v_mov_b64_e32 v[26:27], 0
	v_mov_b64_e32 v[28:29], 0
	v_mov_b64_e32 v[30:31], 0
	v_mov_b64_e32 v[32:33], 0
	v_mov_b64_e32 v[34:35], 0
	v_mov_b64_e32 v[36:37], 0
	v_mov_b64_e32 v[38:39], 0
	v_mov_b64_e32 v[40:41], 0
	v_mov_b64_e32 v[42:43], 0
	v_mov_b64_e32 v[44:45], 0
	v_mov_b64_e32 v[46:47], 0
	v_mov_b64_e32 v[48:49], 0
	v_mov_b64_e32 v[50:51], 0
	v_mov_b64_e32 v[52:53], 0
	v_mov_b64_e32 v[54:55], 0
	v_mov_b32_e32 v57, 0
	v_mov_b64_e32 v[58:59], 0
	v_mov_b64_e32 v[60:61], 0
	v_mov_b64_e32 v[62:63], 0
	v_mov_b64_e32 v[64:65], 0
	v_mov_b64_e32 v[66:67], 0
	v_mov_b64_e32 v[68:69], 0
	v_mov_b64_e32 v[70:71], 0
	v_mov_b64_e32 v[72:73], 0
	v_mov_b64_e32 v[74:75], 0
	v_mov_b64_e32 v[76:77], 0
	v_mov_b64_e32 v[78:79], 0
	v_mov_b64_e32 v[80:81], 0
	v_mov_b64_e32 v[82:83], 0
	v_mov_b64_e32 v[84:85], 0
	v_mov_b64_e32 v[86:87], 0
	v_mov_b64_e32 v[88:89], 0
	v_mov_b64_e32 v[90:91], 0
	v_mov_b64_e32 v[92:93], 0
	v_mov_b64_e32 v[94:95], 0
	v_mov_b64_e32 v[96:97], 0
	v_mov_b64_e32 v[98:99], 0
	v_mov_b64_e32 v[100:101], 0
	v_mov_b64_e32 v[102:103], 0
	v_mov_b64_e32 v[104:105], 0
	v_mov_b64_e32 v[106:107], 0
	v_mov_b64_e32 v[108:109], 0
	v_mov_b64_e32 v[110:111], 0
	v_mov_b64_e32 v[112:113], 0
	v_mov_b64_e32 v[114:115], 0
	v_mov_b64_e32 v[116:117], 0
	v_mov_b64_e32 v[118:119], 0
	v_mov_b64_e32 v[120:121], 0
	v_mov_b64_e32 v[122:123], 0
	v_mov_b64_e32 v[124:125], 0
	v_mov_b64_e32 v[126:127], 0
	.p2align 6

.LBB0_2663:
	s_mov_b32 s15, s7
	s_lshl_b64 s[18:19], s[14:15], 1
	s_add_u32 s18, s58, s18
	s_addc_u32 s19, s59, s19
	s_and_b64 s[20:21], s[0:1], exec
	s_mov_b32 s17, s7
	s_cselect_b32 s6, s19, s25
	s_cselect_b32 s15, s18, s24
	s_lshl_b64 s[20:21], s[16:17], 1
	s_add_u32 s20, s79, s20
	v_readlane_b32 s17, v250, 4
	s_addc_u32 s21, s17, s21
	s_and_b64 s[26:27], s[0:1], exec
	s_cselect_b32 s17, s21, s23
	s_cselect_b32 s54, s20, s22
	s_add_u32 s55, s22, 0x100
	s_addc_u32 s56, s23, 0
	s_add_u32 s22, s24, 0x404000
	v_mov_b32_e32 v0, 0
	s_addc_u32 s23, s25, 0
	s_mov_b32 s64, -2
	v_mov_b32_e32 v1, 0
	v_mov_b64_e32 v[2:3], 0
	v_mov_b64_e32 v[4:5], 0
	v_mov_b64_e32 v[6:7], 0
	v_mov_b64_e32 v[8:9], 0
	v_mov_b64_e32 v[10:11], 0
	v_mov_b64_e32 v[12:13], 0
	v_mov_b64_e32 v[14:15], 0
	v_mov_b64_e32 v[16:17], 0
	v_mov_b64_e32 v[18:19], 0
	v_mov_b64_e32 v[20:21], 0
	v_mov_b64_e32 v[22:23], 0
	v_mov_b64_e32 v[24:25], 0
	v_mov_b64_e32 v[26:27], 0
	v_mov_b64_e32 v[28:29], 0
	v_mov_b64_e32 v[30:31], 0
	v_mov_b64_e32 v[32:33], 0
	v_mov_b64_e32 v[34:35], 0
	v_mov_b64_e32 v[36:37], 0
	v_mov_b64_e32 v[38:39], 0
	v_mov_b64_e32 v[40:41], 0
	v_mov_b64_e32 v[42:43], 0
	v_mov_b64_e32 v[44:45], 0
	v_mov_b64_e32 v[46:47], 0
	v_mov_b64_e32 v[48:49], 0
	v_mov_b64_e32 v[50:51], 0
	v_mov_b64_e32 v[52:53], 0
	v_mov_b64_e32 v[54:55], 0
	v_mov_b64_e32 v[56:57], 0
	v_mov_b64_e32 v[58:59], 0
	v_mov_b64_e32 v[60:61], 0
	v_mov_b64_e32 v[62:63], 0
	v_mov_b64_e32 v[64:65], 0
	v_mov_b64_e32 v[66:67], 0
	v_mov_b64_e32 v[68:69], 0
	v_mov_b64_e32 v[70:71], 0
	v_mov_b64_e32 v[72:73], 0
	v_mov_b64_e32 v[74:75], 0
	v_mov_b64_e32 v[76:77], 0
	v_mov_b64_e32 v[78:79], 0
	v_mov_b64_e32 v[80:81], 0
	v_mov_b64_e32 v[82:83], 0
	v_mov_b64_e32 v[84:85], 0
	v_mov_b64_e32 v[86:87], 0
	v_mov_b64_e32 v[88:89], 0
	v_mov_b64_e32 v[90:91], 0
	v_mov_b64_e32 v[92:93], 0
	v_mov_b64_e32 v[94:95], 0
	v_mov_b64_e32 v[96:97], 0
	v_mov_b64_e32 v[98:99], 0
	v_mov_b64_e32 v[100:101], 0
	v_mov_b64_e32 v[102:103], 0
	v_mov_b64_e32 v[104:105], 0
	v_mov_b64_e32 v[106:107], 0
	v_mov_b64_e32 v[108:109], 0
	v_mov_b64_e32 v[110:111], 0
	v_mov_b64_e32 v[112:113], 0
	v_mov_b64_e32 v[114:115], 0
	v_mov_b64_e32 v[116:117], 0
	v_mov_b64_e32 v[118:119], 0
	v_mov_b64_e32 v[120:121], 0
	v_mov_b64_e32 v[122:123], 0
	v_mov_b64_e32 v[124:125], 0
	v_mov_b64_e32 v[126:127], 0
	.p2align 6

.LBB0_2771:
	s_mov_b32 s27, s11
	s_lshl_b64 s[30:31], s[26:27], 1
	s_add_u32 s30, s91, s30
	s_addc_u32 s31, s92, s31
	s_and_b64 s[34:35], s[8:9], exec
	s_mov_b32 s29, s11
	s_cselect_b32 s10, s31, s7
	s_cselect_b32 s13, s30, s6
	s_lshl_b64 s[34:35], s[28:29], 1
	s_add_u32 s34, s80, s34
	s_addc_u32 s35, s86, s35
	s_and_b64 s[8:9], s[8:9], exec
	s_cselect_b32 s27, s35, s1
	s_cselect_b32 s29, s34, s0
	s_add_u32 s39, s0, 0x100
	s_addc_u32 s40, s1, 0
	s_add_u32 s0, s6, 0x404000
	v_mov_b32_e32 v56, 0
	s_addc_u32 s1, s7, 0
	s_mov_b32 s41, -2
	v_mov_b64_e32 v[0:1], 0
	v_mov_b64_e32 v[2:3], 0
	v_mov_b64_e32 v[4:5], 0
	v_mov_b64_e32 v[6:7], 0
	v_mov_b64_e32 v[8:9], 0
	v_mov_b64_e32 v[10:11], 0
	v_mov_b64_e32 v[12:13], 0
	v_mov_b64_e32 v[14:15], 0
	v_mov_b64_e32 v[16:17], 0
	v_mov_b64_e32 v[18:19], 0
	v_mov_b64_e32 v[20:21], 0
	v_mov_b64_e32 v[22:23], 0
	v_mov_b64_e32 v[24:25], 0
	v_mov_b64_e32 v[26:27], 0
	v_mov_b64_e32 v[28:29], 0
	v_mov_b64_e32 v[30:31], 0
	v_mov_b64_e32 v[32:33], 0
	v_mov_b64_e32 v[34:35], 0
	v_mov_b64_e32 v[36:37], 0
	v_mov_b64_e32 v[38:39], 0
	v_mov_b64_e32 v[40:41], 0
	v_mov_b64_e32 v[42:43], 0
	v_mov_b64_e32 v[44:45], 0
	v_mov_b64_e32 v[46:47], 0
	v_mov_b64_e32 v[48:49], 0
	v_mov_b64_e32 v[50:51], 0
	v_mov_b64_e32 v[52:53], 0
	v_mov_b64_e32 v[54:55], 0
	v_mov_b32_e32 v57, 0
	v_mov_b64_e32 v[58:59], 0
	v_mov_b64_e32 v[60:61], 0
	v_mov_b64_e32 v[62:63], 0
	v_mov_b64_e32 v[64:65], 0
	v_mov_b64_e32 v[66:67], 0
	v_mov_b64_e32 v[68:69], 0
	v_mov_b64_e32 v[70:71], 0
	v_mov_b64_e32 v[72:73], 0
	v_mov_b64_e32 v[74:75], 0
	v_mov_b64_e32 v[76:77], 0
	v_mov_b64_e32 v[78:79], 0
	v_mov_b64_e32 v[80:81], 0
	v_mov_b64_e32 v[82:83], 0
	v_mov_b64_e32 v[84:85], 0
	v_mov_b64_e32 v[86:87], 0
	v_mov_b64_e32 v[88:89], 0
	v_mov_b64_e32 v[90:91], 0
	v_mov_b64_e32 v[92:93], 0
	v_mov_b64_e32 v[94:95], 0
	v_mov_b64_e32 v[96:97], 0
	v_mov_b64_e32 v[98:99], 0
	v_mov_b64_e32 v[100:101], 0
	v_mov_b64_e32 v[102:103], 0
	v_mov_b64_e32 v[104:105], 0
	v_mov_b64_e32 v[106:107], 0
	v_mov_b64_e32 v[108:109], 0
	v_mov_b64_e32 v[110:111], 0
	v_mov_b64_e32 v[112:113], 0
	v_mov_b64_e32 v[114:115], 0
	v_mov_b64_e32 v[116:117], 0
	v_mov_b64_e32 v[118:119], 0
	v_mov_b64_e32 v[120:121], 0
	v_mov_b64_e32 v[122:123], 0
	v_mov_b64_e32 v[124:125], 0
	v_mov_b64_e32 v[126:127], 0
	.p2align 6

.LBB0_2887:
	s_mov_b32 s15, s7
	s_lshl_b64 s[18:19], s[14:15], 1
	s_add_u32 s18, s58, s18
	s_addc_u32 s19, s59, s19
	s_and_b64 s[20:21], s[0:1], exec
	s_mov_b32 s17, s7
	s_cselect_b32 s15, s19, s25
	s_cselect_b32 s50, s18, s24
	s_lshl_b64 s[20:21], s[16:17], 1
	s_add_u32 s20, s4, s20
	s_addc_u32 s21, s5, s21
	s_and_b64 s[26:27], s[0:1], exec
	s_cselect_b32 s17, s21, s23
	s_cselect_b32 s51, s20, s22
	s_add_u32 s52, s22, 0x2c0000
	s_addc_u32 s53, s23, 0
	s_add_u32 s22, s24, 0x404000
	v_mov_b32_e32 v0, 0
	s_addc_u32 s23, s25, 0
	s_mov_b32 s54, -2
	v_mov_b32_e32 v1, 0
	v_mov_b64_e32 v[2:3], 0
	v_mov_b64_e32 v[4:5], 0
	v_mov_b64_e32 v[6:7], 0
	v_mov_b64_e32 v[8:9], 0
	v_mov_b64_e32 v[10:11], 0
	v_mov_b64_e32 v[12:13], 0
	v_mov_b64_e32 v[14:15], 0
	v_mov_b64_e32 v[16:17], 0
	v_mov_b64_e32 v[18:19], 0
	v_mov_b64_e32 v[20:21], 0
	v_mov_b64_e32 v[22:23], 0
	v_mov_b64_e32 v[24:25], 0
	v_mov_b64_e32 v[26:27], 0
	v_mov_b64_e32 v[28:29], 0
	v_mov_b64_e32 v[30:31], 0
	v_mov_b64_e32 v[32:33], 0
	v_mov_b64_e32 v[34:35], 0
	v_mov_b64_e32 v[36:37], 0
	v_mov_b64_e32 v[38:39], 0
	v_mov_b64_e32 v[40:41], 0
	v_mov_b64_e32 v[42:43], 0
	v_mov_b64_e32 v[44:45], 0
	v_mov_b64_e32 v[46:47], 0
	v_mov_b64_e32 v[48:49], 0
	v_mov_b64_e32 v[50:51], 0
	v_mov_b64_e32 v[52:53], 0
	v_mov_b64_e32 v[54:55], 0
	v_mov_b64_e32 v[56:57], 0
	v_mov_b64_e32 v[58:59], 0
	v_mov_b64_e32 v[60:61], 0
	v_mov_b64_e32 v[62:63], 0
	v_mov_b64_e32 v[64:65], 0
	v_mov_b64_e32 v[66:67], 0
	v_mov_b64_e32 v[68:69], 0
	v_mov_b64_e32 v[70:71], 0
	v_mov_b64_e32 v[72:73], 0
	v_mov_b64_e32 v[74:75], 0
	v_mov_b64_e32 v[76:77], 0
	v_mov_b64_e32 v[78:79], 0
	v_mov_b64_e32 v[80:81], 0
	v_mov_b64_e32 v[82:83], 0
	v_mov_b64_e32 v[84:85], 0
	v_mov_b64_e32 v[86:87], 0
	v_mov_b64_e32 v[88:89], 0
	v_mov_b64_e32 v[90:91], 0
	v_mov_b64_e32 v[92:93], 0
	v_mov_b64_e32 v[94:95], 0
	v_mov_b64_e32 v[96:97], 0
	v_mov_b64_e32 v[98:99], 0
	v_mov_b64_e32 v[100:101], 0
	v_mov_b64_e32 v[102:103], 0
	v_mov_b64_e32 v[104:105], 0
	v_mov_b64_e32 v[106:107], 0
	v_mov_b64_e32 v[108:109], 0
	v_mov_b64_e32 v[110:111], 0
	v_mov_b64_e32 v[112:113], 0
	v_mov_b64_e32 v[114:115], 0
	v_mov_b64_e32 v[116:117], 0
	v_mov_b64_e32 v[118:119], 0
	v_mov_b64_e32 v[120:121], 0
	v_mov_b64_e32 v[122:123], 0
	v_mov_b64_e32 v[124:125], 0
	v_mov_b64_e32 v[126:127], 0
	.p2align 6

.LBB0_2965:
	s_mov_b32 s25, s7
	s_lshl_b64 s[26:27], s[24:25], 1
	s_add_u32 s26, s60, s26
	s_addc_u32 s27, s61, s27
	s_and_b64 s[34:35], exec, s[4:5]
	s_cselect_b32 s6, s27, s3
	s_cselect_b32 s9, s26, s2
	s_lshl_b64 s[28:29], s[28:29], 1
	s_add_u32 s28, s23, s28
	s_addc_u32 s29, s44, s29
	s_and_b64 s[4:5], exec, s[4:5]
	s_cselect_b32 s25, s29, s1
	s_cselect_b32 s36, s28, s0
	s_add_u32 s37, s0, 0x80000
	s_addc_u32 s38, s1, 0
	s_add_u32 s0, s2, 0x404000
	v_mov_b32_e32 v88, 0
	s_addc_u32 s1, s3, 0
	s_mov_b32 s39, -2
	v_mov_b64_e32 v[0:1], 0
	v_mov_b64_e32 v[2:3], 0
	v_mov_b64_e32 v[4:5], 0
	v_mov_b64_e32 v[6:7], 0
	v_mov_b64_e32 v[8:9], 0
	v_mov_b64_e32 v[10:11], 0
	v_mov_b64_e32 v[12:13], 0
	v_mov_b64_e32 v[14:15], 0
	v_mov_b64_e32 v[16:17], 0
	v_mov_b64_e32 v[18:19], 0
	v_mov_b64_e32 v[20:21], 0
	v_mov_b64_e32 v[22:23], 0
	v_mov_b64_e32 v[24:25], 0
	v_mov_b64_e32 v[26:27], 0
	v_mov_b64_e32 v[28:29], 0
	v_mov_b64_e32 v[30:31], 0
	v_mov_b64_e32 v[32:33], 0
	v_mov_b64_e32 v[34:35], 0
	v_mov_b64_e32 v[36:37], 0
	v_mov_b64_e32 v[38:39], 0
	v_mov_b64_e32 v[40:41], 0
	v_mov_b64_e32 v[42:43], 0
	v_mov_b64_e32 v[44:45], 0
	v_mov_b64_e32 v[46:47], 0
	v_mov_b64_e32 v[48:49], 0
	v_mov_b64_e32 v[50:51], 0
	v_mov_b64_e32 v[52:53], 0
	v_mov_b64_e32 v[54:55], 0
	v_mov_b64_e32 v[56:57], 0
	v_mov_b64_e32 v[58:59], 0
	v_mov_b64_e32 v[60:61], 0
	v_mov_b64_e32 v[62:63], 0
	v_mov_b64_e32 v[64:65], 0
	v_mov_b64_e32 v[66:67], 0
	v_mov_b64_e32 v[68:69], 0
	v_mov_b64_e32 v[70:71], 0
	v_mov_b64_e32 v[72:73], 0
	v_mov_b64_e32 v[74:75], 0
	v_mov_b64_e32 v[76:77], 0
	v_mov_b64_e32 v[78:79], 0
	v_mov_b64_e32 v[80:81], 0
	v_mov_b64_e32 v[82:83], 0
	v_mov_b64_e32 v[84:85], 0
	v_mov_b64_e32 v[86:87], 0
	v_mov_b32_e32 v89, 0
	v_mov_b64_e32 v[90:91], 0
	v_mov_b64_e32 v[92:93], 0
	v_mov_b64_e32 v[94:95], 0
	v_mov_b64_e32 v[96:97], 0
	v_mov_b64_e32 v[98:99], 0
	v_mov_b64_e32 v[100:101], 0
	v_mov_b64_e32 v[102:103], 0
	v_mov_b64_e32 v[104:105], 0
	v_mov_b64_e32 v[106:107], 0
	v_mov_b64_e32 v[108:109], 0
	v_mov_b64_e32 v[110:111], 0
	v_mov_b64_e32 v[112:113], 0
	v_mov_b64_e32 v[114:115], 0
	v_mov_b64_e32 v[116:117], 0
	v_mov_b64_e32 v[118:119], 0
	v_mov_b64_e32 v[120:121], 0
	v_mov_b64_e32 v[122:123], 0
	v_mov_b64_e32 v[124:125], 0
	v_mov_b64_e32 v[126:127], 0
	.p2align 6
